# stack8 + P9 dot reduction on DPP/permlane32 (one LDS round trip per batch instead of six)
# speedup vs baseline: 1.0103x; 1.0103x over previous
.LpA_half:
	s_cmp_lt_u32 s34, 8
	s_cselect_b64 s[2:3], -1, 0
	s_waitcnt vmcnt(8)
	v_mov_b32_e32 v51, v2
	v_mov_b32_e32 v52, v3
	v_mov_b32_e32 v53, v4
	s_waitcnt vmcnt(8)
	v_cvt_scalef32_pk32_f32_fp6 v[2:33], v[48:53], 1.0
	s_waitcnt lgkmcnt(14)
	v_fma_f32 v37, v215, v2, 0
	v_fma_f32 v38, v215, v18, 0
	v_fmac_f32_e32 v37, v216, v3
	v_fmac_f32_e32 v38, v216, v19
	s_waitcnt lgkmcnt(13)
	v_fmac_f32_e32 v37, v217, v4
	v_fmac_f32_e32 v38, v217, v20
	s_waitcnt lgkmcnt(12)
	v_fmac_f32_e32 v37, v218, v5
	v_fmac_f32_e32 v38, v218, v21
	s_waitcnt lgkmcnt(11)
	v_fmac_f32_e32 v37, v219, v6
	v_fmac_f32_e32 v38, v219, v22
	s_waitcnt lgkmcnt(10)
	v_fmac_f32_e32 v37, v220, v7
	v_fmac_f32_e32 v38, v220, v23
	s_waitcnt lgkmcnt(9)
	v_fmac_f32_e32 v37, v221, v8
	v_fmac_f32_e32 v38, v221, v24
	s_waitcnt lgkmcnt(8)
	v_fmac_f32_e32 v37, v222, v9
	v_fmac_f32_e32 v38, v222, v25
	s_waitcnt lgkmcnt(7)
	v_fmac_f32_e32 v37, v223, v10
	v_fmac_f32_e32 v38, v223, v26
	s_waitcnt lgkmcnt(6)
	v_fmac_f32_e32 v37, v224, v11
	v_fmac_f32_e32 v38, v224, v27
	s_waitcnt lgkmcnt(5)
	v_fmac_f32_e32 v37, v225, v12
	v_fmac_f32_e32 v38, v225, v28
	s_waitcnt lgkmcnt(4)
	v_fmac_f32_e32 v37, v226, v13
	v_fmac_f32_e32 v38, v226, v29
	s_waitcnt lgkmcnt(3)
	v_fmac_f32_e32 v37, v227, v14
	v_fmac_f32_e32 v38, v227, v30
	s_waitcnt lgkmcnt(2)
	v_fmac_f32_e32 v37, v228, v15
	v_fmac_f32_e32 v38, v228, v31
	s_waitcnt lgkmcnt(1)
	v_fmac_f32_e32 v37, v229, v16
	v_fmac_f32_e32 v38, v229, v32
	s_waitcnt vmcnt(8)
	v_mov_b32_e32 v57, v80
	v_mov_b32_e32 v58, v81
	v_mov_b32_e32 v59, v82
	s_waitcnt lgkmcnt(0)
	v_fmac_f32_e32 v37, v230, v17
	v_fmac_f32_e32 v38, v230, v33
	s_waitcnt vmcnt(8)
	v_cvt_scalef32_pk32_f32_fp6 v[2:33], v[54:59], 1.0
	v_fma_f32 v39, v215, v2, 0
	v_fma_f32 v43, v215, v18, 0
	v_fmac_f32_e32 v39, v216, v3
	v_fmac_f32_e32 v43, v216, v19
	v_fmac_f32_e32 v39, v217, v4
	v_fmac_f32_e32 v43, v217, v20
	v_fmac_f32_e32 v39, v218, v5
	v_fmac_f32_e32 v43, v218, v21
	v_fmac_f32_e32 v39, v219, v6
	v_fmac_f32_e32 v43, v219, v22
	v_fmac_f32_e32 v39, v220, v7
	v_fmac_f32_e32 v43, v220, v23
	v_fmac_f32_e32 v39, v221, v8
	v_fmac_f32_e32 v43, v221, v24
	v_fmac_f32_e32 v39, v222, v9
	v_fmac_f32_e32 v43, v222, v25
	v_fmac_f32_e32 v39, v223, v10
	v_fmac_f32_e32 v43, v223, v26
	v_fmac_f32_e32 v39, v224, v11
	v_fmac_f32_e32 v43, v224, v27
	v_fmac_f32_e32 v39, v225, v12
	v_fmac_f32_e32 v43, v225, v28
	v_fmac_f32_e32 v39, v226, v13
	v_fmac_f32_e32 v43, v226, v29
	v_fmac_f32_e32 v39, v227, v14
	v_fmac_f32_e32 v43, v227, v30
	v_fmac_f32_e32 v39, v228, v15
	v_fmac_f32_e32 v43, v228, v31
	v_fmac_f32_e32 v39, v229, v16
	v_fmac_f32_e32 v43, v229, v32
	s_waitcnt vmcnt(8)
	v_mov_b32_e32 v63, v84
	v_mov_b32_e32 v64, v85
	v_mov_b32_e32 v65, v86
	v_fmac_f32_e32 v39, v230, v17
	v_fmac_f32_e32 v43, v230, v33
	s_waitcnt vmcnt(8)
	v_cvt_scalef32_pk32_f32_fp6 v[2:33], v[60:65], 1.0
	v_fma_f32 v47, v215, v2, 0
	v_fma_f32 v48, v215, v18, 0
	v_fmac_f32_e32 v47, v216, v3
	v_fmac_f32_e32 v48, v216, v19
	v_fmac_f32_e32 v47, v217, v4
	v_fmac_f32_e32 v48, v217, v20
	v_fmac_f32_e32 v47, v218, v5
	v_fmac_f32_e32 v48, v218, v21
	v_fmac_f32_e32 v47, v219, v6
	v_fmac_f32_e32 v48, v219, v22
	v_fmac_f32_e32 v47, v220, v7
	v_fmac_f32_e32 v48, v220, v23
	v_fmac_f32_e32 v47, v221, v8
	v_fmac_f32_e32 v48, v221, v24
	v_fmac_f32_e32 v47, v222, v9
	v_fmac_f32_e32 v48, v222, v25
	v_fmac_f32_e32 v47, v223, v10
	v_fmac_f32_e32 v48, v223, v26
	v_fmac_f32_e32 v47, v224, v11
	v_fmac_f32_e32 v48, v224, v27
	v_fmac_f32_e32 v47, v225, v12
	v_fmac_f32_e32 v48, v225, v28
	v_fmac_f32_e32 v47, v226, v13
	v_fmac_f32_e32 v48, v226, v29
	v_fmac_f32_e32 v47, v227, v14
	v_fmac_f32_e32 v48, v227, v30
	v_fmac_f32_e32 v47, v228, v15
	v_fmac_f32_e32 v48, v228, v31
	v_fmac_f32_e32 v47, v229, v16
	v_fmac_f32_e32 v48, v229, v32
	s_waitcnt vmcnt(8)
	v_mov_b32_e32 v79, v88
	v_mov_b32_e32 v80, v89
	v_mov_b32_e32 v81, v90
	v_fmac_f32_e32 v47, v230, v17
	v_fmac_f32_e32 v48, v230, v33
	v_cvt_scalef32_pk32_f32_fp6 v[2:33], v[76:81], 1.0
	v_fma_f32 v2, v215, v2, 0
	v_fma_f32 v18, v215, v18, 0
	v_fmac_f32_e32 v2, v216, v3
	v_fmac_f32_e32 v18, v216, v19
	v_fmac_f32_e32 v2, v217, v4
	v_fmac_f32_e32 v18, v217, v20
	v_fmac_f32_e32 v2, v218, v5
	v_fmac_f32_e32 v18, v218, v21
	v_fmac_f32_e32 v2, v219, v6
	v_fmac_f32_e32 v18, v219, v22
	v_fmac_f32_e32 v2, v220, v7
	v_fmac_f32_e32 v18, v220, v23
	v_fmac_f32_e32 v2, v221, v8
	v_fmac_f32_e32 v18, v221, v24
	v_fmac_f32_e32 v2, v222, v9
	v_fmac_f32_e32 v18, v222, v25
	v_fmac_f32_e32 v2, v223, v10
	v_fmac_f32_e32 v18, v223, v26
	v_fmac_f32_e32 v2, v224, v11
	v_fmac_f32_e32 v18, v224, v27
	v_fmac_f32_e32 v2, v225, v12
	v_fmac_f32_e32 v18, v225, v28
	v_fmac_f32_e32 v2, v226, v13
	v_fmac_f32_e32 v18, v226, v29
	v_fmac_f32_e32 v2, v227, v14
	v_fmac_f32_e32 v18, v227, v30
	v_fmac_f32_e32 v2, v228, v15
	v_fmac_f32_e32 v18, v228, v31
	v_fmac_f32_e32 v2, v229, v16
	v_fmac_f32_e32 v18, v229, v32
	v_fmac_f32_e32 v2, v230, v17
	v_fmac_f32_e32 v18, v230, v33
	v_cndmask_b32_e64 v3, v37, v38, s[0:1]
	v_cndmask_b32_e64 v5, v39, v43, s[0:1]
	v_cndmask_b32_e64 v6, v47, v48, s[0:1]
	v_cndmask_b32_e64 v7, v2, v18, s[0:1]
	v_cndmask_b32_e64 v4, v38, v37, s[0:1]
	s_nop 0
	v_mov_b32_dpp v3, v3 quad_perm:[1,0,3,2] row_mask:0xf bank_mask:0xf
	v_mov_b32_dpp v5, v5 quad_perm:[1,0,3,2] row_mask:0xf bank_mask:0xf
	v_mov_b32_dpp v6, v6 quad_perm:[1,0,3,2] row_mask:0xf bank_mask:0xf
	v_mov_b32_dpp v7, v7 quad_perm:[1,0,3,2] row_mask:0xf bank_mask:0xf
	v_add_f32_e32 v3, v4, v3
	v_cndmask_b32_e64 v4, v43, v39, s[0:1]
	v_add_f32_e32 v4, v4, v5
	v_cndmask_b32_e64 v5, v48, v47, s[0:1]
	v_cndmask_b32_e64 v2, v18, v2, s[0:1]
	v_add_f32_e32 v5, v5, v6
	v_add_f32_e32 v2, v2, v7
	v_cndmask_b32_e32 v6, v3, v4, vcc
	v_cndmask_b32_e32 v7, v5, v2, vcc
	v_cndmask_b32_e32 v3, v4, v3, vcc
	v_cndmask_b32_e32 v2, v2, v5, vcc
	v_and_or_b32 v5, s33, 56, v231
	v_mov_b32_dpp v6, v6 quad_perm:[2,3,0,1] row_mask:0xf bank_mask:0xf
	v_mov_b32_dpp v7, v7 quad_perm:[2,3,0,1] row_mask:0xf bank_mask:0xf
	v_add_f32_e32 v3, v3, v6
	v_add_f32_e32 v2, v2, v7
	v_cndmask_b32_e64 v4, v3, v2, s[4:5]
	v_cndmask_b32_e64 v2, v2, v3, s[4:5]
	v_lshlrev_b32_e32 v5, 2, v5
	v_cndmask_b32_e64 v7, v214, v213, s[2:3]
	v_mov_b32_dpp v6, v4 row_shl:4 row_mask:0xf bank_mask:0x5
	v_mov_b32_dpp v6, v4 row_shr:4 row_mask:0xf bank_mask:0xa
	ds_bpermute_b32 v7, v5, v7
	v_add_f32_e32 v2, v2, v6
	s_nop 1
	v_mov_b32_dpp v3, v2 row_ror:8 row_mask:0xf bank_mask:0xf
	v_add_f32_e32 v2, v2, v3
	ds_bpermute_b32 v3, v209, v2
	s_waitcnt lgkmcnt(0)
	v_add_f32_e32 v3, v2, v3
	v_mov_b32_e32 v2, v7
	v_mov_b32_e32 v4, v3
	s_nop 1
	v_permlane32_swap_b32 v3, v4
	v_add_f32_e32 v3, v3, v4
	v_mul_f32_e32 v3, 0x3caaaaab, v3
	v_mul_f32_e32 v4, 0x3f3504f3, v3
	v_cmp_nlt_f32_e64 s[2:3], |v4|, 1.0
	s_and_saveexec_b64 s[14:15], s[2:3]
	s_xor_b64 s[14:15], exec, s[14:15]
	s_cbranch_execz .LpA_erf_else
	v_fma_f32 v5, |v4|, s7, v203
	v_fma_f32 v5, |v4|, v5, s13
	v_fma_f32 v5, |v4|, v5, s17
	v_fma_f32 v5, |v4|, v5, s19
	v_fma_f32 v5, |v4|, v5, s21
	v_fma_f32 v5, |v4|, v5, s23
	v_fma_f32 v5, |v4|, v5, |v4|
	v_mul_f32_e32 v6, 0xbfb8aa3b, v5
	v_fma_f32 v7, v5, s25, -v6
	v_rndne_f32_e32 v8, v6
	v_fmac_f32_e32 v7, 0xb2a5705f, v5
	v_sub_f32_e32 v6, v6, v8
	v_add_f32_e32 v6, v6, v7
	v_cvt_i32_f32_e32 v7, v8
	v_exp_f32_e32 v6, v6
	v_cmp_nlt_f32_e64 s[2:3], s27, v5
	v_ldexp_f32 v6, v6, v7
	s_nop 0
	v_cndmask_b32_e64 v6, 0, v6, s[2:3]
	v_cmp_ngt_f32_e64 s[2:3], s28, v5
	s_nop 1
	v_cndmask_b32_e64 v5, v204, v6, s[2:3]
	v_sub_f32_e32 v5, 1.0, v5
